# attention unit start: KX-table global loads kept in flight across the unit-start barrier; their LDS writes happen after the first K/V DMA wait (one round trip instead of two per unit)
# speedup vs baseline: 1.0054x; 1.0054x over previous
; #define DMA_K(t, slot) glds16(ksrc + (long)(t) * KVBLK * KP, (unsigned)__builtin_amdgcn_readfirstlane(kdst + (slot)))
; #define DMA_V(t, slot) glds16(vsrc + (long)(t) * KVBLK * KP, (unsigned)__builtin_amdgcn_readfirstlane(vdst + (slot)))
; #define LAS __attribute__((address_space(3)))
; #define KARG(i) ({ unsigned long long p_; asm volatile("s_load_dwordx2 %0, %1, %2\n\ts_waitcnt lgkmcnt(0)" : "=s"(p_) : "s"((unsigned long long)__builtin_amdgcn_kernarg_segment_ptr()), "n"((i) * 8)); p_; })
; template <int THRL> __device__ __forceinline__ void attn_unit(int b, int h, int qb, const bf16* Q, const bf16* __restrict__ K, const bf16* __restrict__ V, bf16* O, char* shm, bool first, int qb_next, bf16x8& qn0, bf16x8& qn1, bf16x8& qn2, bf16x8& qn3) {
;     ...
;     if (first) { DMA_K(0, 0); DMA_V(0, 0); DMA_K(1, SLOTB); } else { DMA_V(0, 0); }
;     bf16x8 qr[4];
; __global__ void __launch_bounds__(NWAVES * 64, 2) mk_fwd(Args args) {
;     ...
;                 LAS v4u* kxt = (LAS v4u*)(lds + attn_body::LDS_KX); const v4u* src = (const v4u*)((const unsigned char*)KARG(20) + WS_KXG) + (size_t)bh * SEQ;
; #pragma unroll
;                 for (int j = 0; j < 4; ++j) kxt[tid + 512 * j] = src[tid + 512 * j];
;                 if (tid == 0) { unsigned zz = 0u; asm volatile("" : "+v"(zz)); kxt[SEQ] = (v4u){zz, zz, zz, zz}; }
;                 __syncthreads();
.LBB0_238:
	s_ashr_i32 s6, s85, 1
	s_ashr_i32 s7, s6, 31
	s_load_dwordx2 s[8:9], s[0:1], 0xa0
	s_waitcnt lgkmcnt(0)
	s_lshl_b64 s[34:35], s[6:7], 15
	s_add_u32 s8, s8, s34
	s_addc_u32 s9, s9, s35
	v_lshl_add_u64 v[4:5], v[200:201], 4, s[8:9]
	v_add_co_u32_e32 v0, vcc, 0x1c800000, v4
	s_nop 1
	v_addc_co_u32_e32 v1, vcc, 0, v5, vcc
	global_load_dwordx4 v[116:119], v[0:1], off
	v_add_co_u32_e32 v6, vcc, 0x1c802000, v4
	s_nop 1
	v_addc_co_u32_e32 v7, vcc, 0, v5, vcc
	global_load_dwordx4 v[120:123], v[6:7], off
	v_add_co_u32_e32 v6, vcc, 0x1c804000, v4
	s_nop 1
	v_addc_co_u32_e32 v7, vcc, 0, v5, vcc
	global_load_dwordx4 v[124:127], v[6:7], off
	v_add_co_u32_e32 v4, vcc, 0x1c806000, v4
	s_nop 1
	v_addc_co_u32_e32 v5, vcc, 0, v5, vcc
	global_load_dwordx4 v[128:131], v[4:5], off
	s_waitcnt lgkmcnt(0)
	s_and_saveexec_b64 s[8:9], s[4:5]
	s_cbranch_execz .LBB0_240
	v_mov_b32_e32 v0, v99
	v_mov_b32_e32 v4, s83
	v_mov_b32_e32 v1, v0
	v_mov_b32_e32 v2, v0
	v_mov_b32_e32 v3, v0
	ds_write_b128 v4, v[0:3]

; #define WAIT_BAR(N) asm volatile("s_waitcnt vmcnt(" #N ") lgkmcnt(0)\n\ts_barrier" ::: "memory")
; #define DMA_K(t, slot) glds16(ksrc + (long)(t) * KVBLK * KP, (unsigned)__builtin_amdgcn_readfirstlane(kdst + (slot)))
; #define DMA_V(t, slot) glds16(vsrc + (long)(t) * KVBLK * KP, (unsigned)__builtin_amdgcn_readfirstlane(vdst + (slot)))
; #define KXRD(tt) do { const lds_cptr p_ = kxp + (tt) * kxstep; kx[0] = *(L3BF8*)(p_); kx[1] = *(L3BF8*)(p_ + kxoff2); } while (0)
; template <int THRL> __device__ __forceinline__ void attn_unit(int b, int h, int qb, const bf16* Q, const bf16* __restrict__ K, const bf16* __restrict__ V, bf16* O, char* shm, bool first, int qb_next, bf16x8& qn0, bf16x8& qn1, bf16x8& qn2, bf16x8& qn3) {
;     ...
;     if (first) { DMA_K(0, 0); DMA_V(0, 0); DMA_K(1, SLOTB); } else { DMA_V(0, 0); }
;     bf16x8 qr[4];
;     if (first) {
; #pragma unroll
;         for (int d0 = 0; d0 < 4; ++d0) qr[d0] = *reinterpret_cast<const bf16x8*>(&Qw[(long)r32 * KP + d0 * 16 + hi * 8]);
;     } else { qr[0] = qn0; qr[1] = qn1; qr[2] = qn2; qr[3] = qn3; }
;     const int qrel = wid * QBLK + r32;
;     float mhat = 0.f, l_reg = 0.f; f32x16 o[2]; o[0] = f32x16{}; o[1] = f32x16{}; const f32x16 negm = f32x16{}; bf16x8 qx = make_qx(0.f, hi);
;     ...
;     bool resc = false;
;     ...
;     f32x16 pA0, pA1, pB0, pB1;
;     int sl_prev = 0, sl_cur = 0, sl_next = SLOTB;
;     ...
;     if (first) { DMA_K(2, 2 * SLOTB); WAIT_BAR(3); }
;     else { WAIT_BAR(1); }
;     KXRD(0);
.LBB0_264:
	s_lshl_b32 s67, s66, 8
	s_lshl_b32 s93, s91, 5
	v_and_b32_e32 v232, 31, v66
	s_or_b32 s42, s36, s67
	s_ashr_i32 s94, s93, 31
	s_add_u32 s58, s42, s93
	v_mul_u32_u24_e32 v0, 0xa00, v232
	s_waitcnt vmcnt(0)
	s_mov_b64 exec, s[62:63]
	ds_write_b128 v221, v[116:119]
	ds_write_b128 v222, v[120:123]
	ds_write_b128 v223, v[124:127]
	ds_write_b128 v224, v[128:131]
	s_mov_b64 exec, -1
	v_mov_b64_e32 v[130:131], v[102:103]
	v_mov_b64_e32 v[126:127], v[106:107]
	v_mov_b64_e32 v[122:123], v[110:111]
	v_mov_b64_e32 v[118:119], v[114:115]
	v_lshrrev_b32_e32 v233, 5, v231
	s_addc_u32 s59, s37, s94
	s_andn2_b64 vcc, exec, s[62:63]
	v_lshlrev_b32_e32 v202, 1, v0
	v_mov_b64_e32 v[128:129], v[100:101]
	v_mov_b64_e32 v[124:125], v[104:105]
	v_mov_b64_e32 v[120:121], v[108:109]
	v_mov_b64_e32 v[116:117], v[112:113]
	s_cbranch_vccz .LBB0_347
	s_mov_b64 s[62:63], -1
	s_and_b64 vcc, exec, s[6:7]
	s_cbranch_vccnz .LBB0_348
